# GEMM1 epilogue: store addresses from one base plus constant strides (per-store 64-bit multiply-adds removed)
# baseline (speedup 1.0000x reference)
; __device__ __forceinline__ unsigned pk2(float lo, float hi) { return cvt_pk_bf16(lo, hi); }
; __device__ __forceinline__ void store_tile_bf16(const f32x4 (&acc)[4][4], unsigned char* smem, bf16_t* dst, size_t ld, int m0, int n0, int tid, int wr, int wc, int g, int lr) {
; #pragma unroll
;     for (int i = 0; i < 4; ++i)
; #pragma unroll
;         for (int j = 0; j < 4; ++j) {
;             const int row = wr * 64 + 16 * i + lr, col = wc * 64 + 16 * j + 4 * g;
;             uint2 w; w.x = pk2(acc[i][j][0], acc[i][j][1]); w.y = pk2(acc[i][j][2], acc[i][j][3]);
;             *(uint2*)(smem + row * 272 + col * 2) = w;
;         }
;     __syncthreads();
; #pragma unroll
;     for (int q = 0; q < 8; ++q) {
;         const int id = tid + 256 * q, row = id >> 4, ch = id & 15;
;         const uint4 v = *(const uint4*)(smem + row * 272 + ch * 16);
;         *(uint4*)(dst + (size_t)(m0 + row) * ld + n0 + ch * 8) = v;
;     }
;     __syncthreads();
; }
.LBB0_181:
	v_lshl_or_b32 v66, v81, 6, v80
	v_lshlrev_b32_e32 v68, 3, v83
	v_lshl_add_u32 v69, v82, 7, 0
	v_mul_lo_u32 v66, v66, s23
	s_ashr_i32 s11, s10, 31
	v_add3_u32 v66, v69, v68, v66
	v_cvt_pk_bf16_f32 v62, v62, v63
	v_cvt_pk_bf16_f32 v63, v64, v65
	v_cvt_pk_bf16_f32 v58, v58, v59
	v_cvt_pk_bf16_f32 v59, v60, v61
	v_cvt_pk_bf16_f32 v54, v54, v55
	v_cvt_pk_bf16_f32 v55, v56, v57
	v_cvt_pk_bf16_f32 v50, v50, v51
	v_cvt_pk_bf16_f32 v51, v52, v53
	s_lshl_b64 s[0:1], s[10:11], 1
	ds_write2_b64 v66, v[62:63], v[58:59] offset1:4
	ds_write2_b64 v66, v[54:55], v[50:51] offset0:8 offset1:12
	v_cvt_pk_bf16_f32 v42, v42, v43
	v_cvt_pk_bf16_f32 v43, v44, v45
	v_add_u32_e32 v44, 0x1000, v66
	v_cvt_pk_bf16_f32 v26, v26, v27
	v_cvt_pk_bf16_f32 v27, v28, v29
	v_add_u32_e32 v28, 0x2000, v66
	v_cvt_pk_bf16_f32 v14, v14, v15
	v_cvt_pk_bf16_f32 v15, v16, v17
	v_cvt_pk_bf16_f32 v10, v10, v11
	v_cvt_pk_bf16_f32 v11, v12, v13
	v_add_u32_e32 v12, 0x3000, v66
	v_cvt_pk_bf16_f32 v6, v6, v7
	v_cvt_pk_bf16_f32 v7, v8, v9
	v_cvt_pk_bf16_f32 v2, v2, v3
	v_cvt_pk_bf16_f32 v3, v4, v5
	v_lshlrev_b32_e32 v66, 4, v80
	s_add_u32 s0, s7, s0
	ds_write2_b64 v12, v[14:15], v[10:11] offset0:96 offset1:100
	ds_write2_b64 v12, v[6:7], v[2:3] offset0:104 offset1:108
	v_add_u32_e32 v10, 0, v66
	s_addc_u32 s1, s9, s1
	s_mov_b64 s[98:99], s[0:1]
	v_ashrrev_i32_e32 v6, 4, v79
	v_lshl_add_u64 v[12:13], s[0:1], 0, v[66:67]
	v_mad_u64_u32 v[2:3], s[0:1], v6, s23, v[10:11]
	v_add_u32_e32 v6, s42, v6
	v_cvt_pk_bf16_f32 v46, v46, v47
	v_cvt_pk_bf16_f32 v47, v48, v49
	v_cvt_pk_bf16_f32 v38, v38, v39
	v_cvt_pk_bf16_f32 v39, v40, v41
	v_cvt_pk_bf16_f32 v34, v34, v35
	v_cvt_pk_bf16_f32 v35, v36, v37
	v_cvt_pk_bf16_f32 v30, v30, v31
	v_cvt_pk_bf16_f32 v31, v32, v33
	v_cvt_pk_bf16_f32 v22, v22, v23
	v_cvt_pk_bf16_f32 v23, v24, v25
	v_cvt_pk_bf16_f32 v18, v18, v19
	v_cvt_pk_bf16_f32 v19, v20, v21
	v_mad_u32_u24 v234, v6, s34, v66
	v_add_u32_e32 v6, 0x100, v79
	ds_write2_b64 v44, v[46:47], v[42:43] offset0:32 offset1:36
	ds_write2_b64 v44, v[38:39], v[34:35] offset0:40 offset1:44
	ds_write2_b64 v28, v[30:31], v[26:27] offset0:64 offset1:68
	ds_write2_b64 v28, v[22:23], v[18:19] offset0:72 offset1:76
	s_waitcnt lgkmcnt(0)
	s_barrier
	v_mov_b32_e32 v230, v2
	ds_read_b128 v[2:5], v230
	ds_read_b128 v[6:9], v230 offset:4352
	s_add_i32 s35, s35, s33
	s_cmp_ge_i32 s35, s14
	v_add_u32_e32 v235, 0x1c000, v234
	s_waitcnt lgkmcnt(1)
	global_store_dwordx4 v234, v[2:5], s[98:99]
	s_waitcnt lgkmcnt(0)
	global_store_dwordx4 v235, v[6:9], s[98:99]
	v_add_u32_e32 v234, 0x38000, v234
	v_add_u32_e32 v235, 0x38000, v235
	ds_read_b128 v[2:5], v230 offset:8704
	ds_read_b128 v[6:9], v230 offset:13056
	s_waitcnt lgkmcnt(1)
	global_store_dwordx4 v234, v[2:5], s[98:99]
	s_waitcnt lgkmcnt(0)
	global_store_dwordx4 v235, v[6:9], s[98:99]
	v_add_u32_e32 v234, 0x38000, v234
	v_add_u32_e32 v235, 0x38000, v235
	ds_read_b128 v[2:5], v230 offset:17408
	ds_read_b128 v[6:9], v230 offset:21760
	s_waitcnt lgkmcnt(1)
	global_store_dwordx4 v234, v[2:5], s[98:99]
	s_waitcnt lgkmcnt(0)
	global_store_dwordx4 v235, v[6:9], s[98:99]
	v_add_u32_e32 v234, 0x38000, v234
	v_add_u32_e32 v235, 0x38000, v235
	ds_read_b128 v[2:5], v230 offset:26112
	ds_read_b128 v[6:9], v230 offset:30464
	s_waitcnt lgkmcnt(1)
	global_store_dwordx4 v234, v[2:5], s[98:99]
	s_waitcnt lgkmcnt(0)
	global_store_dwordx4 v235, v[6:9], s[98:99]
	s_barrier
	s_cbranch_scc1 .LBB0_184
